# added: proj main first K-iteration peeled with C=0 MFMAs (no accumulator zeroing pass); HALFN loop no longer stages the never-read B half-tile (waits vmcnt(8)->vmcnt(6))
# speedup vs baseline: 1.0224x; 1.0006x over previous
; #define PG8_STAGE(bufoff, gbase, voff) do { _Pragma("unroll") for (int _i = 0; _i < 2; ++_i) \
;         __builtin_amdgcn_global_load_lds((const unsigned*)((const char*)(gbase) + (voff)[_i]), (LAS unsigned*)(lds + (bufoff) + ldsw + _i * 8192), 16, 0, 0); } while (0)
; #define PG8_LDA(dst, b, h) do { _Pragma("unroll") for (int m = 0; m < 4; ++m) _Pragma("unroll") for (int k = 0; k < 2; ++k) dst[m][k] = *(const LAS bf16x8*)(lds + PG8_SA(b, h) + aoff + m * 2048 + k * 1024); } while (0)
; #define PG8_LDB(dst, b, h) do { _Pragma("unroll") for (int n = 0; n < 2; ++n) _Pragma("unroll") for (int k = 0; k < 2; ++k) dst[n][k] = *(const LAS bf16x8*)(lds + PG8_SB(b, h) + boff + n * 2048 + k * 1024); } while (0)
; #define PG8_WAIT_V(n) asm volatile("s_waitcnt vmcnt(" #n ")" ::: "memory")
; template <class Epi, class Order = StaticOrder, bool HALFN = false>
; __device__ __forceinline__ void gemm_phase(LAS unsigned char* lds, const Gemm g, const Epi& E) {
;     ...
;         const bool has_next = S.next(ui + 1, nxt);
;         const char* nA = has_next ? (const char*)g.A + (size_t)nxt.pm * tstepA + (size_t)nxt.pn * g.a_pn_off * 2 : cA; const char* nB = has_next ? (const char*)g.Bt + (size_t)nxt.pn * tstepB + (HALFN ? (size_t)(nxt.half - 1) * hstepB : (size_t)0) : cB;
; #pragma unroll 1
;         for (int t = 0; t < nt; t += 2) {
;             const bool last = (t == nt - 2);
;             if constexpr (Epi::SEAMS) { if (t == Epi::SEAM0 || t == Epi::SEAM1) E.seam(acc, cur, t == Epi::SEAM0 ? 0 : 1, wr, wc, fr, fq); }
;             const char* a1 = cA + (size_t)(t + 1) * kstep;
;             const char* a2 = last ? nA : cA + (size_t)(t + 2) * kstep; const char* b2 = last ? nB : cB + (size_t)(t + 2) * kstep;
;             const char* a3 = a2 + kstep; const char* b3 = b2 + kstep;
;             PG8_LDB(B0, 0, 0); if constexpr (!HALFN) PG8_LDB(B1, 0, 1); PG8_SCHED; PG8_LDA(At, 0, 0); PG8_STAGE(PG8_SA(1, 1), a1 + hstepA, voffA);
;             PG8_WAIT_V(8); PG8_WAIT_L(0); PG8_BAR; PG8_MMA(0, 0, At, B0); if constexpr (!HALFN) PG8_MMA(0, 1, At, B1); PG8_BAR; PG8_SCHED;
;             PG8_LDA(At, 0, 1); PG8_STAGE(PG8_SB(0, 0), b2, voffB); PG8_STAGE(PG8_SB(0, 1), b2 + hstepB, voffB); PG8_STAGE(PG8_SA(0, 0), a2, voffA);
;             PG8_WAIT_V(8); PG8_WAIT_L(0); PG8_BAR; PG8_MMA(1, 0, At, B0); if constexpr (!HALFN) PG8_MMA(1, 1, At, B1); PG8_BAR; PG8_SCHED;
.LBB0_193:
	s_mov_b32 s48, s18
	s_ashr_i32 s49, s18, 31
	s_lshl_b64 s[6:7], s[48:49], 20
	s_add_u32 s74, s0, s6
	s_addc_u32 s75, s1, s7
	s_mov_b32 s50, s9
	s_and_b64 s[6:7], s[54:55], exec
	s_cselect_b32 s8, s75, s63
	s_cselect_b32 s9, s74, s62
	s_ashr_i32 s51, s50, 31
	s_lshl_b64 s[6:7], s[50:51], 20
	s_add_u32 s92, s10, s6
	s_addc_u32 s93, s11, s7
	s_and_b64 s[6:7], s[54:55], exec
	s_cselect_b32 s18, s93, s5
	s_cselect_b32 s19, s92, s4
	s_add_u32 s62, s62, 0x80080
	s_addc_u32 s63, s63, 0
	s_add_u32 s20, s4, 0x100
	s_addc_u32 s21, s5, 0
	s_mov_b32 s22, -2
	s_add_u32 s4, s62, 0xfff80080
	s_addc_u32 s5, s63, -1
	s_add_i32 s23, 0, 0x10000
	s_cmp_eq_u32 s22, 28
	s_cselect_b32 s7, s8, s5
	s_cselect_b32 s6, s9, s4
	v_add_u32_e32 v142, s23, v145
	s_cselect_b32 s5, s18, s21
	s_cselect_b32 s4, s19, s20
	s_add_i32 s26, 0, 0x14000
	ds_read_b128 v[148:151], v142
	ds_read_b128 v[152:155], v142 offset:1024
	ds_read_b128 v[156:159], v142 offset:2048
	ds_read_b128 v[168:171], v142 offset:3072
	v_add_u32_e32 v142, s26, v145
	ds_read_b128 v[172:175], v142
	ds_read_b128 v[176:179], v142 offset:1024
	ds_read_b128 v[180:183], v142 offset:2048
	ds_read_b128 v[184:187], v142 offset:3072
	v_lshl_add_u64 v[160:161], s[62:63], 0, v[138:139]
	s_add_i32 m0, s53, 0xc000
	ds_read_b128 v[208:211], v147
	ds_read_b128 v[212:215], v147 offset:1024
	ds_read_b128 v[216:219], v147 offset:2048
	ds_read_b128 v[220:223], v147 offset:3072
	ds_read_b128 v[224:227], v147 offset:4096
	ds_read_b128 v[228:231], v147 offset:5120
	ds_read_b128 v[232:235], v147 offset:6144
	ds_read_b128 v[236:239], v147 offset:7168
	global_load_lds_dwordx4 v[160:161], off
	v_lshl_add_u64 v[160:161], s[62:63], 0, v[140:141]
	s_add_i32 m0, s53, 0xe000
	s_nop 0
	global_load_lds_dwordx4 v[160:161], off
	s_waitcnt vmcnt(8)
	s_waitcnt lgkmcnt(0)
	s_barrier
	s_setprio 1
	s_waitcnt lgkmcnt(0)
	v_mfma_f32_16x16x32_bf16 v[126:129], v[148:151], v[208:211], 0
	v_mfma_f32_16x16x32_bf16 v[122:125], v[156:159], v[208:211], 0
	v_mfma_f32_16x16x32_bf16 v[114:117], v[148:151], v[216:219], 0
	v_mfma_f32_16x16x32_bf16 v[106:109], v[156:159], v[216:219], 0
	v_mfma_f32_16x16x32_bf16 v[102:105], v[148:151], v[224:227], 0
	v_mfma_f32_16x16x32_bf16 v[94:97], v[156:159], v[224:227], 0
	v_mfma_f32_16x16x32_bf16 v[86:89], v[148:151], v[232:235], 0
	v_mfma_f32_16x16x32_bf16 v[78:81], v[156:159], v[232:235], 0
	v_mfma_f32_16x16x32_bf16 v[126:129], v[152:155], v[212:215], v[126:129]
	v_mfma_f32_16x16x32_bf16 v[122:125], v[168:171], v[212:215], v[122:125]
	v_mfma_f32_16x16x32_bf16 v[114:117], v[152:155], v[220:223], v[114:117]
	v_mfma_f32_16x16x32_bf16 v[106:109], v[168:171], v[220:223], v[106:109]
	v_mfma_f32_16x16x32_bf16 v[102:105], v[152:155], v[228:231], v[102:105]
	v_mfma_f32_16x16x32_bf16 v[94:97], v[168:171], v[228:231], v[94:97]
	v_mfma_f32_16x16x32_bf16 v[86:89], v[152:155], v[236:239], v[86:89]
	v_mfma_f32_16x16x32_bf16 v[78:81], v[168:171], v[236:239], v[78:81]
	s_setprio 0
	s_setprio 1
	v_mfma_f32_16x16x32_bf16 v[118:121], v[172:175], v[208:211], 0
	v_mfma_f32_16x16x32_bf16 v[110:113], v[180:183], v[208:211], 0
	v_mfma_f32_16x16x32_bf16 v[98:101], v[172:175], v[216:219], 0
	v_mfma_f32_16x16x32_bf16 v[90:93], v[180:183], v[216:219], 0
	v_mfma_f32_16x16x32_bf16 v[82:85], v[172:175], v[224:227], 0
	v_mfma_f32_16x16x32_bf16 v[74:77], v[180:183], v[224:227], 0
	v_mfma_f32_16x16x32_bf16 v[70:73], v[172:175], v[232:235], 0
	v_mfma_f32_16x16x32_bf16 v[66:69], v[180:183], v[232:235], 0
	v_mfma_f32_16x16x32_bf16 v[118:121], v[176:179], v[212:215], v[118:121]
	v_mfma_f32_16x16x32_bf16 v[110:113], v[184:187], v[212:215], v[110:113]
	v_mfma_f32_16x16x32_bf16 v[98:101], v[176:179], v[220:223], v[98:101]
	v_mfma_f32_16x16x32_bf16 v[90:93], v[184:187], v[220:223], v[90:93]
	v_mfma_f32_16x16x32_bf16 v[82:85], v[176:179], v[228:231], v[82:85]
	v_mfma_f32_16x16x32_bf16 v[74:77], v[184:187], v[228:231], v[74:77]
	v_mfma_f32_16x16x32_bf16 v[70:73], v[176:179], v[236:239], v[70:73]
	v_mfma_f32_16x16x32_bf16 v[66:69], v[184:187], v[236:239], v[66:69]
	s_setprio 0
	s_barrier
	s_add_i32 s23, s23, s56
	v_lshl_add_u64 v[160:161], s[4:5], 0, v[132:133]
	s_mov_b32 m0, s23
	ds_read_b128 v[208:211], v147 offset:16384
	ds_read_b128 v[212:215], v147 offset:17408
	ds_read_b128 v[216:219], v147 offset:18432
	ds_read_b128 v[220:223], v147 offset:19456
	ds_read_b128 v[224:227], v147 offset:20480
	ds_read_b128 v[228:231], v147 offset:21504
	ds_read_b128 v[232:235], v147 offset:22528
	ds_read_b128 v[236:239], v147 offset:23552
	global_load_lds_dwordx4 v[160:161], off
	s_add_i32 m0, s23, 0x2000
	s_add_u32 s24, s4, 0x80000
	v_lshl_add_u64 v[240:241], s[4:5], 0, v[136:137]
	s_addc_u32 s25, s5, 0
	s_add_i32 s23, s26, s56
	global_load_lds_dwordx4 v[240:241], off
	v_lshl_add_u64 v[242:243], s[24:25], 0, v[132:133]
	s_mov_b32 m0, s23
	v_lshl_add_u64 v[244:245], s[6:7], 0, v[134:135]
	global_load_lds_dwordx4 v[242:243], off
	v_lshl_add_u64 v[242:243], s[24:25], 0, v[136:137]
	s_add_i32 m0, s23, 0x2000
	s_nop 0
	global_load_lds_dwordx4 v[242:243], off
	v_lshl_add_u64 v[242:243], s[6:7], 0, v[130:131]
	s_mov_b32 m0, s53
	s_nop 0
	global_load_lds_dwordx4 v[242:243], off
	s_mov_b32 m0, s80
	s_nop 0
	global_load_lds_dwordx4 v[244:245], off
	s_waitcnt vmcnt(8)
	s_waitcnt lgkmcnt(0)
	s_barrier
; #define PG8_STAGE(bufoff, gbase, voff) do { _Pragma("unroll") for (int _i = 0; _i < 2; ++_i) \
;         __builtin_amdgcn_global_load_lds((const unsigned*)((const char*)(gbase) + (voff)[_i]), (LAS unsigned*)(lds + (bufoff) + ldsw + _i * 8192), 16, 0, 0); } while (0)
; #define PG8_LDA(dst, b, h) do { _Pragma("unroll") for (int m = 0; m < 4; ++m) _Pragma("unroll") for (int k = 0; k < 2; ++k) dst[m][k] = *(const LAS bf16x8*)(lds + PG8_SA(b, h) + aoff + m * 2048 + k * 1024); } while (0)
; #define PG8_LDB(dst, b, h) do { _Pragma("unroll") for (int n = 0; n < 2; ++n) _Pragma("unroll") for (int k = 0; k < 2; ++k) dst[n][k] = *(const LAS bf16x8*)(lds + PG8_SB(b, h) + boff + n * 2048 + k * 1024); } while (0)
; #define PG8_MMA(ai, bj, At, Bt) do { __builtin_amdgcn_s_setprio(1); _Pragma("unroll") for (int m = 0; m < 4; ++m) _Pragma("unroll") for (int n = 0; n < 2; ++n) _Pragma("unroll") for (int k = 0; k < 2; ++k) \
;         acc[ai][bj][m][n] = __builtin_amdgcn_mfma_f32_16x16x32_bf16(Bt[n][k], At[m][k], acc[ai][bj][m][n], 0, 0, 0); __builtin_amdgcn_s_setprio(0); } while (0)
; #define PG8_WAIT_V(n) asm volatile("s_waitcnt vmcnt(" #n ")" ::: "memory")
; #define PG8_WAIT_L(n) asm volatile("s_waitcnt lgkmcnt(" #n ")" ::: "memory")
; #define PG8_BAR __builtin_amdgcn_s_barrier()
; #define PG8_SCHED __builtin_amdgcn_sched_barrier(0)
; template <class Epi, class Order = StaticOrder, bool HALFN = false>
; __device__ __forceinline__ void gemm_phase(LAS unsigned char* lds, const Gemm g, const Epi& E) {
;     ...
;             PG8_WAIT_V(8); PG8_WAIT_L(0); PG8_BAR; PG8_MMA(1, 0, At, B0); if constexpr (!HALFN) PG8_MMA(1, 1, At, B1); PG8_BAR; PG8_SCHED;
;             PG8_LDB(B0, 1, 0); if constexpr (!HALFN) PG8_LDB(B1, 1, 1); PG8_SCHED; PG8_LDA(At, 1, 0); PG8_STAGE(PG8_SA(0, 1), a2 + hstepA, voffA);
;             PG8_WAIT_V(8); PG8_WAIT_L(0); PG8_BAR; PG8_MMA(0, 0, At, B0); if constexpr (!HALFN) PG8_MMA(0, 1, At, B1); PG8_BAR; PG8_SCHED;
	s_setprio 1
	s_waitcnt lgkmcnt(0)
	v_mfma_f32_16x16x32_bf16 v[62:65], v[148:151], v[208:211], 0
	v_mfma_f32_16x16x32_bf16 v[58:61], v[156:159], v[208:211], 0
	v_mfma_f32_16x16x32_bf16 v[54:57], v[148:151], v[216:219], 0
	v_mfma_f32_16x16x32_bf16 v[46:49], v[156:159], v[216:219], 0
	v_mfma_f32_16x16x32_bf16 v[38:41], v[148:151], v[224:227], 0
	v_mfma_f32_16x16x32_bf16 v[30:33], v[156:159], v[224:227], 0
	v_mfma_f32_16x16x32_bf16 v[22:25], v[148:151], v[232:235], 0
	v_mfma_f32_16x16x32_bf16 v[14:17], v[156:159], v[232:235], 0
	v_mfma_f32_16x16x32_bf16 v[62:65], v[152:155], v[212:215], v[62:65]
	v_mfma_f32_16x16x32_bf16 v[58:61], v[168:171], v[212:215], v[58:61]
	v_mfma_f32_16x16x32_bf16 v[54:57], v[152:155], v[220:223], v[54:57]
	v_mfma_f32_16x16x32_bf16 v[46:49], v[168:171], v[220:223], v[46:49]
	v_mfma_f32_16x16x32_bf16 v[38:41], v[152:155], v[228:231], v[38:41]
	v_mfma_f32_16x16x32_bf16 v[30:33], v[168:171], v[228:231], v[30:33]
	v_mfma_f32_16x16x32_bf16 v[22:25], v[152:155], v[236:239], v[22:25]
	v_mfma_f32_16x16x32_bf16 v[14:17], v[168:171], v[236:239], v[14:17]
	s_setprio 0
	s_setprio 1
	v_mfma_f32_16x16x32_bf16 v[50:53], v[172:175], v[208:211], 0
	v_mfma_f32_16x16x32_bf16 v[42:45], v[180:183], v[208:211], 0
	v_mfma_f32_16x16x32_bf16 v[34:37], v[172:175], v[216:219], 0
	v_mfma_f32_16x16x32_bf16 v[26:29], v[180:183], v[216:219], 0
	v_mfma_f32_16x16x32_bf16 v[18:21], v[172:175], v[224:227], 0
	v_mfma_f32_16x16x32_bf16 v[10:13], v[180:183], v[224:227], 0
	v_mfma_f32_16x16x32_bf16 v[6:9], v[172:175], v[232:235], 0
	v_mfma_f32_16x16x32_bf16 v[2:5], v[180:183], v[232:235], 0
	v_mfma_f32_16x16x32_bf16 v[50:53], v[176:179], v[212:215], v[50:53]
	v_mfma_f32_16x16x32_bf16 v[42:45], v[184:187], v[212:215], v[42:45]
	v_mfma_f32_16x16x32_bf16 v[34:37], v[176:179], v[220:223], v[34:37]
	v_mfma_f32_16x16x32_bf16 v[26:29], v[184:187], v[220:223], v[26:29]
	v_mfma_f32_16x16x32_bf16 v[18:21], v[176:179], v[228:231], v[18:21]
	v_mfma_f32_16x16x32_bf16 v[10:13], v[184:187], v[228:231], v[10:13]
	v_mfma_f32_16x16x32_bf16 v[6:9], v[176:179], v[236:239], v[6:9]
	v_mfma_f32_16x16x32_bf16 v[2:5], v[184:187], v[236:239], v[2:5]
	s_setprio 0
	s_barrier
	s_add_i32 s23, 0, 0x18000
	v_add_u32_e32 v142, s23, v145
	s_add_i32 s24, 0, 0x1c000
	ds_read_b128 v[148:151], v142
	ds_read_b128 v[152:155], v142 offset:1024
	ds_read_b128 v[156:159], v142 offset:2048
	ds_read_b128 v[168:171], v142 offset:3072
	v_add_u32_e32 v142, s24, v145
	ds_read_b128 v[172:175], v142
	ds_read_b128 v[176:179], v142 offset:1024
	ds_read_b128 v[180:183], v142 offset:2048
	ds_read_b128 v[184:187], v142 offset:3072
	s_add_u32 s6, s6, 0x80000
	s_addc_u32 s7, s7, 0
	s_mov_b32 m0, s81
	v_lshl_add_u64 v[246:247], s[6:7], 0, v[130:131]
	ds_read_b128 v[208:211], v147 offset:32768
	ds_read_b128 v[212:215], v147 offset:33792
	ds_read_b128 v[216:219], v147 offset:34816
	ds_read_b128 v[220:223], v147 offset:35840
	ds_read_b128 v[224:227], v147 offset:36864
	ds_read_b128 v[228:231], v147 offset:37888
	ds_read_b128 v[232:235], v147 offset:38912
	ds_read_b128 v[236:239], v147 offset:39936
	global_load_lds_dwordx4 v[246:247], off
	v_lshl_add_u64 v[246:247], s[6:7], 0, v[134:135]
	s_mov_b32 m0, s82
	s_nop 0
	global_load_lds_dwordx4 v[246:247], off
	s_waitcnt vmcnt(8)
	s_waitcnt lgkmcnt(0)
	s_barrier
	s_setprio 1
	s_waitcnt lgkmcnt(0)
	v_mfma_f32_16x16x32_bf16 v[126:129], v[148:151], v[208:211], v[126:129]
	v_mfma_f32_16x16x32_bf16 v[122:125], v[156:159], v[208:211], v[122:125]
	v_mfma_f32_16x16x32_bf16 v[114:117], v[148:151], v[216:219], v[114:117]
	v_mfma_f32_16x16x32_bf16 v[106:109], v[156:159], v[216:219], v[106:109]
	v_mfma_f32_16x16x32_bf16 v[102:105], v[148:151], v[224:227], v[102:105]
	v_mfma_f32_16x16x32_bf16 v[94:97], v[156:159], v[224:227], v[94:97]
	v_mfma_f32_16x16x32_bf16 v[86:89], v[148:151], v[232:235], v[86:89]
	v_mfma_f32_16x16x32_bf16 v[78:81], v[156:159], v[232:235], v[78:81]
	v_mfma_f32_16x16x32_bf16 v[126:129], v[152:155], v[212:215], v[126:129]
	v_mfma_f32_16x16x32_bf16 v[122:125], v[168:171], v[212:215], v[122:125]
	v_mfma_f32_16x16x32_bf16 v[114:117], v[152:155], v[220:223], v[114:117]
	v_mfma_f32_16x16x32_bf16 v[106:109], v[168:171], v[220:223], v[106:109]
	v_mfma_f32_16x16x32_bf16 v[102:105], v[152:155], v[228:231], v[102:105]
	v_mfma_f32_16x16x32_bf16 v[94:97], v[168:171], v[228:231], v[94:97]
	v_mfma_f32_16x16x32_bf16 v[86:89], v[152:155], v[236:239], v[86:89]
	v_mfma_f32_16x16x32_bf16 v[78:81], v[168:171], v[236:239], v[78:81]
	s_setprio 0
	s_setprio 1
	v_mfma_f32_16x16x32_bf16 v[118:121], v[172:175], v[208:211], v[118:121]
	v_mfma_f32_16x16x32_bf16 v[110:113], v[180:183], v[208:211], v[110:113]
	v_mfma_f32_16x16x32_bf16 v[98:101], v[172:175], v[216:219], v[98:101]
	v_mfma_f32_16x16x32_bf16 v[90:93], v[180:183], v[216:219], v[90:93]
	v_mfma_f32_16x16x32_bf16 v[82:85], v[172:175], v[224:227], v[82:85]
	v_mfma_f32_16x16x32_bf16 v[74:77], v[180:183], v[224:227], v[74:77]
	v_mfma_f32_16x16x32_bf16 v[70:73], v[172:175], v[232:235], v[70:73]
	v_mfma_f32_16x16x32_bf16 v[66:69], v[180:183], v[232:235], v[66:69]
	v_mfma_f32_16x16x32_bf16 v[118:121], v[176:179], v[212:215], v[118:121]
	v_mfma_f32_16x16x32_bf16 v[110:113], v[184:187], v[212:215], v[110:113]
	v_mfma_f32_16x16x32_bf16 v[98:101], v[176:179], v[220:223], v[98:101]
	v_mfma_f32_16x16x32_bf16 v[90:93], v[184:187], v[220:223], v[90:93]
	v_mfma_f32_16x16x32_bf16 v[82:85], v[176:179], v[228:231], v[82:85]
	v_mfma_f32_16x16x32_bf16 v[74:77], v[184:187], v[228:231], v[74:77]
	v_mfma_f32_16x16x32_bf16 v[70:73], v[176:179], v[236:239], v[70:73]
	v_mfma_f32_16x16x32_bf16 v[66:69], v[184:187], v[236:239], v[66:69]
	s_setprio 0
	s_barrier
; #define PG8_STAGE(bufoff, gbase, voff) do { _Pragma("unroll") for (int _i = 0; _i < 2; ++_i) \
;         __builtin_amdgcn_global_load_lds((const unsigned*)((const char*)(gbase) + (voff)[_i]), (LAS unsigned*)(lds + (bufoff) + ldsw + _i * 8192), 16, 0, 0); } while (0)
; #define PG8_LDA(dst, b, h) do { _Pragma("unroll") for (int m = 0; m < 4; ++m) _Pragma("unroll") for (int k = 0; k < 2; ++k) dst[m][k] = *(const LAS bf16x8*)(lds + PG8_SA(b, h) + aoff + m * 2048 + k * 1024); } while (0)
; #define PG8_MMA(ai, bj, At, Bt) do { __builtin_amdgcn_s_setprio(1); _Pragma("unroll") for (int m = 0; m < 4; ++m) _Pragma("unroll") for (int n = 0; n < 2; ++n) _Pragma("unroll") for (int k = 0; k < 2; ++k) \
;         acc[ai][bj][m][n] = __builtin_amdgcn_mfma_f32_16x16x32_bf16(Bt[n][k], At[m][k], acc[ai][bj][m][n], 0, 0, 0); __builtin_amdgcn_s_setprio(0); } while (0)
; #define PG8_WAIT_V(n) asm volatile("s_waitcnt vmcnt(" #n ")" ::: "memory")
; #define PG8_WAIT_L(n) asm volatile("s_waitcnt lgkmcnt(" #n ")" ::: "memory")
; #define PG8_BAR __builtin_amdgcn_s_barrier()
; #define PG8_SCHED __builtin_amdgcn_sched_barrier(0)
; template <class Epi, class Order = StaticOrder, bool HALFN = false>
; __device__ __forceinline__ void gemm_phase(LAS unsigned char* lds, const Gemm g, const Epi& E) {
;     ...
;             PG8_LDA(At, 1, 1); PG8_STAGE(PG8_SB(1, 0), b3, voffB); PG8_STAGE(PG8_SB(1, 1), b3 + hstepB, voffB); PG8_STAGE(PG8_SA(1, 0), a3, voffA);
;             PG8_WAIT_V(8); PG8_WAIT_L(0); PG8_BAR; PG8_MMA(1, 0, At, B0); if constexpr (!HALFN) PG8_MMA(1, 1, At, B1); PG8_BAR; PG8_SCHED;
;         }
	s_add_i32 s6, s23, s56
	v_lshl_add_u64 v[160:161], v[160:161], 0, s[60:61]
	s_mov_b32 m0, s6
	ds_read_b128 v[208:211], v147 offset:49152
	ds_read_b128 v[212:215], v147 offset:50176
	ds_read_b128 v[216:219], v147 offset:51200
	ds_read_b128 v[220:223], v147 offset:52224
	ds_read_b128 v[224:227], v147 offset:53248
	ds_read_b128 v[228:231], v147 offset:54272
	ds_read_b128 v[232:235], v147 offset:55296
	ds_read_b128 v[236:239], v147 offset:56320
	global_load_lds_dwordx4 v[160:161], off
	s_add_i32 m0, s6, 0x2000
	s_add_u32 s4, s4, 0x80080
	v_lshl_add_u64 v[160:161], v[240:241], 0, s[60:61]
	s_addc_u32 s5, s5, 0
	s_add_i32 s6, s24, s56
	global_load_lds_dwordx4 v[160:161], off
	v_lshl_add_u64 v[160:161], s[4:5], 0, v[132:133]
	s_mov_b32 m0, s6
	s_nop 0
	global_load_lds_dwordx4 v[160:161], off
	v_lshl_add_u64 v[160:161], s[4:5], 0, v[136:137]
	s_add_i32 m0, s6, 0x2000
	s_nop 0
	global_load_lds_dwordx4 v[160:161], off
	v_lshl_add_u64 v[160:161], v[242:243], 0, s[60:61]
	s_mov_b32 m0, s95
	s_nop 0
	global_load_lds_dwordx4 v[160:161], off
	v_lshl_add_u64 v[160:161], v[244:245], 0, s[60:61]
	s_mov_b32 m0, s15
	s_nop 0
	global_load_lds_dwordx4 v[160:161], off
	s_waitcnt vmcnt(8)
	s_waitcnt lgkmcnt(0)
	s_barrier
	s_setprio 1
	s_waitcnt lgkmcnt(0)
	v_mfma_f32_16x16x32_bf16 v[62:65], v[148:151], v[208:211], v[62:65]
	v_mfma_f32_16x16x32_bf16 v[58:61], v[156:159], v[208:211], v[58:61]
	v_mfma_f32_16x16x32_bf16 v[54:57], v[148:151], v[216:219], v[54:57]
	v_mfma_f32_16x16x32_bf16 v[46:49], v[156:159], v[216:219], v[46:49]
	v_mfma_f32_16x16x32_bf16 v[38:41], v[148:151], v[224:227], v[38:41]
	v_mfma_f32_16x16x32_bf16 v[30:33], v[156:159], v[224:227], v[30:33]
	v_mfma_f32_16x16x32_bf16 v[22:25], v[148:151], v[232:235], v[22:25]
	v_mfma_f32_16x16x32_bf16 v[14:17], v[156:159], v[232:235], v[14:17]
	v_mfma_f32_16x16x32_bf16 v[62:65], v[152:155], v[212:215], v[62:65]
	v_mfma_f32_16x16x32_bf16 v[58:61], v[168:171], v[212:215], v[58:61]
	v_mfma_f32_16x16x32_bf16 v[54:57], v[152:155], v[220:223], v[54:57]
	v_mfma_f32_16x16x32_bf16 v[46:49], v[168:171], v[220:223], v[46:49]
	v_mfma_f32_16x16x32_bf16 v[38:41], v[152:155], v[228:231], v[38:41]
	v_mfma_f32_16x16x32_bf16 v[30:33], v[168:171], v[228:231], v[30:33]
	v_mfma_f32_16x16x32_bf16 v[22:25], v[152:155], v[236:239], v[22:25]
	v_mfma_f32_16x16x32_bf16 v[14:17], v[168:171], v[236:239], v[14:17]
	s_setprio 0
	s_setprio 1
	v_mfma_f32_16x16x32_bf16 v[50:53], v[172:175], v[208:211], v[50:53]
	v_mfma_f32_16x16x32_bf16 v[42:45], v[180:183], v[208:211], v[42:45]
	v_mfma_f32_16x16x32_bf16 v[34:37], v[172:175], v[216:219], v[34:37]
	v_mfma_f32_16x16x32_bf16 v[26:29], v[180:183], v[216:219], v[26:29]
	v_mfma_f32_16x16x32_bf16 v[18:21], v[172:175], v[224:227], v[18:21]
	v_mfma_f32_16x16x32_bf16 v[10:13], v[180:183], v[224:227], v[10:13]
	v_mfma_f32_16x16x32_bf16 v[6:9], v[172:175], v[232:235], v[6:9]
	v_mfma_f32_16x16x32_bf16 v[2:5], v[180:183], v[232:235], v[2:5]
	v_mfma_f32_16x16x32_bf16 v[50:53], v[176:179], v[212:215], v[50:53]
	v_mfma_f32_16x16x32_bf16 v[42:45], v[184:187], v[212:215], v[42:45]
	v_mfma_f32_16x16x32_bf16 v[34:37], v[176:179], v[220:223], v[34:37]
	v_mfma_f32_16x16x32_bf16 v[26:29], v[184:187], v[220:223], v[26:29]
	v_mfma_f32_16x16x32_bf16 v[18:21], v[176:179], v[228:231], v[18:21]
	v_mfma_f32_16x16x32_bf16 v[10:13], v[184:187], v[228:231], v[10:13]
	v_mfma_f32_16x16x32_bf16 v[6:9], v[176:179], v[236:239], v[6:9]
	v_mfma_f32_16x16x32_bf16 v[2:5], v[184:187], v[236:239], v[2:5]
	s_setprio 0
	s_barrier
	s_add_i32 s22, s22, 2
	s_add_u32 s62, s62, 0x100
	s_addc_u32 s63, s63, 0
	s_add_u32 s20, s20, 0x100
	s_addc_u32 s21, s21, 0
	s_cmp_gt_u32 s22, 29

; #define PG8_STAGE(bufoff, gbase, voff) do { _Pragma("unroll") for (int _i = 0; _i < 2; ++_i) \
;         __builtin_amdgcn_global_load_lds((const unsigned*)((const char*)(gbase) + (voff)[_i]), (LAS unsigned*)(lds + (bufoff) + ldsw + _i * 8192), 16, 0, 0); } while (0)
; #define PG8_LDA(dst, b, h) do { _Pragma("unroll") for (int m = 0; m < 4; ++m) _Pragma("unroll") for (int k = 0; k < 2; ++k) dst[m][k] = *(const LAS bf16x8*)(lds + PG8_SA(b, h) + aoff + m * 2048 + k * 1024); } while (0)
; #define PG8_LDB(dst, b, h) do { _Pragma("unroll") for (int n = 0; n < 2; ++n) _Pragma("unroll") for (int k = 0; k < 2; ++k) dst[n][k] = *(const LAS bf16x8*)(lds + PG8_SB(b, h) + boff + n * 2048 + k * 1024); } while (0)
; #define PG8_MMA(ai, bj, At, Bt) do { __builtin_amdgcn_s_setprio(1); _Pragma("unroll") for (int m = 0; m < 4; ++m) _Pragma("unroll") for (int n = 0; n < 2; ++n) _Pragma("unroll") for (int k = 0; k < 2; ++k) \
;         acc[ai][bj][m][n] = __builtin_amdgcn_mfma_f32_16x16x32_bf16(Bt[n][k], At[m][k], acc[ai][bj][m][n], 0, 0, 0); __builtin_amdgcn_s_setprio(0); } while (0)
; #define PG8_WAIT_V(n) asm volatile("s_waitcnt vmcnt(" #n ")" ::: "memory")
; #define PG8_WAIT_L(n) asm volatile("s_waitcnt lgkmcnt(" #n ")" ::: "memory")
; #define PG8_BAR __builtin_amdgcn_s_barrier()
; #define PG8_SCHED __builtin_amdgcn_sched_barrier(0)
; template <class Epi, class Order = StaticOrder, bool HALFN = false>
; __device__ __forceinline__ void gemm_phase(LAS unsigned char* lds, const Gemm g, const Epi& E) {
;     ...
;             const char* a1 = cA + (size_t)(t + 1) * kstep;
;             const char* a2 = last ? nA : cA + (size_t)(t + 2) * kstep; const char* b2 = last ? nB : cB + (size_t)(t + 2) * kstep;
;             const char* a3 = a2 + kstep; const char* b3 = b2 + kstep;
;             PG8_LDB(B0, 0, 0); if constexpr (!HALFN) PG8_LDB(B1, 0, 1); PG8_SCHED; PG8_LDA(At, 0, 0); PG8_STAGE(PG8_SA(1, 1), a1 + hstepA, voffA);
;             PG8_WAIT_V(8); PG8_WAIT_L(0); PG8_BAR; PG8_MMA(0, 0, At, B0); if constexpr (!HALFN) PG8_MMA(0, 1, At, B1); PG8_BAR; PG8_SCHED;
;             PG8_LDA(At, 0, 1); PG8_STAGE(PG8_SB(0, 0), b2, voffB); PG8_STAGE(PG8_SB(0, 1), b2 + hstepB, voffB); PG8_STAGE(PG8_SA(0, 0), a2, voffA);
;             PG8_WAIT_V(8); PG8_WAIT_L(0); PG8_BAR; PG8_MMA(1, 0, At, B0); if constexpr (!HALFN) PG8_MMA(1, 1, At, B1); PG8_BAR; PG8_SCHED;
.LBB0_239:
	s_add_u32 s4, vcc_lo, 0xfff80080
	s_addc_u32 s5, vcc_hi, -1
	s_add_i32 s34, 0, 0x10000
	v_add_u32_e32 v78, s34, v81
	ds_read_b128 v[84:87], v78
	ds_read_b128 v[88:91], v78 offset:1024
	ds_read_b128 v[92:95], v78 offset:2048
	ds_read_b128 v[96:99], v78 offset:3072
	s_cmp_eq_u32 s31, 28
	s_cselect_b32 s9, s25, s5
	s_cselect_b32 s8, s26, s4
	s_cselect_b32 s5, s27, s30
	s_cselect_b32 s4, s28, s29
	v_lshl_add_u64 v[132:133], vcc, 0, v[74:75]
	s_add_i32 m0, s16, 0xc000
	ds_read_b128 v[100:103], v83
	ds_read_b128 v[104:107], v83 offset:1024
	ds_read_b128 v[108:111], v83 offset:2048
	ds_read_b128 v[112:115], v83 offset:3072
	ds_read_b128 v[116:119], v83 offset:4096
	ds_read_b128 v[120:123], v83 offset:5120
	ds_read_b128 v[124:127], v83 offset:6144
	ds_read_b128 v[128:131], v83 offset:7168
	global_load_lds_dwordx4 v[132:133], off
	v_lshl_add_u64 v[132:133], vcc, 0, v[76:77]
	s_add_i32 m0, s16, 0xe000
	s_nop 0
	global_load_lds_dwordx4 v[132:133], off
	s_waitcnt vmcnt(6)
	s_waitcnt lgkmcnt(0)
	s_barrier
	s_setprio 1
	s_waitcnt lgkmcnt(0)
	v_mfma_f32_16x16x32_bf16 v[62:65], v[84:87], v[100:103], v[62:65]
	v_mfma_f32_16x16x32_bf16 v[58:61], v[92:95], v[100:103], v[58:61]
	v_mfma_f32_16x16x32_bf16 v[54:57], v[84:87], v[108:111], v[54:57]
	v_mfma_f32_16x16x32_bf16 v[50:53], v[92:95], v[108:111], v[50:53]
	v_mfma_f32_16x16x32_bf16 v[46:49], v[84:87], v[116:119], v[46:49]
	v_mfma_f32_16x16x32_bf16 v[42:45], v[92:95], v[116:119], v[42:45]
	v_mfma_f32_16x16x32_bf16 v[38:41], v[84:87], v[124:127], v[38:41]
	v_mfma_f32_16x16x32_bf16 v[34:37], v[92:95], v[124:127], v[34:37]
	v_mfma_f32_16x16x32_bf16 v[62:65], v[88:91], v[104:107], v[62:65]
	v_mfma_f32_16x16x32_bf16 v[58:61], v[96:99], v[104:107], v[58:61]
	v_mfma_f32_16x16x32_bf16 v[54:57], v[88:91], v[112:115], v[54:57]
	v_mfma_f32_16x16x32_bf16 v[50:53], v[96:99], v[112:115], v[50:53]
	v_mfma_f32_16x16x32_bf16 v[46:49], v[88:91], v[120:123], v[46:49]
	v_mfma_f32_16x16x32_bf16 v[42:45], v[96:99], v[120:123], v[42:45]
	v_mfma_f32_16x16x32_bf16 v[38:41], v[88:91], v[128:131], v[38:41]
	v_mfma_f32_16x16x32_bf16 v[34:37], v[96:99], v[128:131], v[34:37]
	s_setprio 0
	s_barrier
	s_add_i32 s34, s34, s15
	v_lshl_add_u64 v[132:133], s[4:5], 0, v[68:69]
	s_mov_b32 m0, s34
	ds_read_b128 v[100:103], v83 offset:16384
	ds_read_b128 v[104:107], v83 offset:17408
	ds_read_b128 v[108:111], v83 offset:18432
	ds_read_b128 v[112:115], v83 offset:19456
	ds_read_b128 v[116:119], v83 offset:20480
	ds_read_b128 v[120:123], v83 offset:21504
	ds_read_b128 v[124:127], v83 offset:22528
	ds_read_b128 v[128:131], v83 offset:23552
	global_load_lds_dwordx4 v[132:133], off
	s_add_i32 m0, s34, 0x2000
	s_add_u32 s34, s4, 0x80000
	v_lshl_add_u64 v[134:135], s[4:5], 0, v[72:73]
	s_addc_u32 s35, s5, 0
	global_load_lds_dwordx4 v[134:135], off
	v_lshl_add_u64 v[138:139], s[8:9], 0, v[70:71]
	v_lshl_add_u64 v[136:137], s[8:9], 0, v[66:67]
	s_mov_b32 m0, s16
	s_nop 0
	global_load_lds_dwordx4 v[136:137], off
	s_mov_b32 m0, s19
	s_nop 0
	global_load_lds_dwordx4 v[138:139], off
	s_waitcnt vmcnt(6)
	s_waitcnt lgkmcnt(0)
	s_barrier
	s_setprio 1
	s_waitcnt lgkmcnt(0)
	v_mfma_f32_16x16x32_bf16 v[30:33], v[84:87], v[100:103], v[30:33]
	v_mfma_f32_16x16x32_bf16 v[26:29], v[92:95], v[100:103], v[26:29]
	v_mfma_f32_16x16x32_bf16 v[22:25], v[84:87], v[108:111], v[22:25]
	v_mfma_f32_16x16x32_bf16 v[18:21], v[92:95], v[108:111], v[18:21]
	v_mfma_f32_16x16x32_bf16 v[14:17], v[84:87], v[116:119], v[14:17]
	v_mfma_f32_16x16x32_bf16 v[10:13], v[92:95], v[116:119], v[10:13]
	v_mfma_f32_16x16x32_bf16 v[6:9], v[84:87], v[124:127], v[6:9]
	v_mfma_f32_16x16x32_bf16 v[2:5], v[92:95], v[124:127], v[2:5]
	v_mfma_f32_16x16x32_bf16 v[30:33], v[88:91], v[104:107], v[30:33]
	v_mfma_f32_16x16x32_bf16 v[26:29], v[96:99], v[104:107], v[26:29]
	v_mfma_f32_16x16x32_bf16 v[22:25], v[88:91], v[112:115], v[22:25]
	v_mfma_f32_16x16x32_bf16 v[18:21], v[96:99], v[112:115], v[18:21]
	v_mfma_f32_16x16x32_bf16 v[14:17], v[88:91], v[120:123], v[14:17]
	v_mfma_f32_16x16x32_bf16 v[10:13], v[96:99], v[120:123], v[10:13]
	v_mfma_f32_16x16x32_bf16 v[6:9], v[88:91], v[128:131], v[6:9]
	v_mfma_f32_16x16x32_bf16 v[2:5], v[96:99], v[128:131], v[2:5]
	s_setprio 0
	s_barrier
; #define PG8_STAGE(bufoff, gbase, voff) do { _Pragma("unroll") for (int _i = 0; _i < 2; ++_i) \
;         __builtin_amdgcn_global_load_lds((const unsigned*)((const char*)(gbase) + (voff)[_i]), (LAS unsigned*)(lds + (bufoff) + ldsw + _i * 8192), 16, 0, 0); } while (0)
; #define PG8_LDA(dst, b, h) do { _Pragma("unroll") for (int m = 0; m < 4; ++m) _Pragma("unroll") for (int k = 0; k < 2; ++k) dst[m][k] = *(const LAS bf16x8*)(lds + PG8_SA(b, h) + aoff + m * 2048 + k * 1024); } while (0)
; #define PG8_LDB(dst, b, h) do { _Pragma("unroll") for (int n = 0; n < 2; ++n) _Pragma("unroll") for (int k = 0; k < 2; ++k) dst[n][k] = *(const LAS bf16x8*)(lds + PG8_SB(b, h) + boff + n * 2048 + k * 1024); } while (0)
; #define PG8_MMA(ai, bj, At, Bt) do { __builtin_amdgcn_s_setprio(1); _Pragma("unroll") for (int m = 0; m < 4; ++m) _Pragma("unroll") for (int n = 0; n < 2; ++n) _Pragma("unroll") for (int k = 0; k < 2; ++k) \
;         acc[ai][bj][m][n] = __builtin_amdgcn_mfma_f32_16x16x32_bf16(Bt[n][k], At[m][k], acc[ai][bj][m][n], 0, 0, 0); __builtin_amdgcn_s_setprio(0); } while (0)
; #define PG8_WAIT_V(n) asm volatile("s_waitcnt vmcnt(" #n ")" ::: "memory")
; #define PG8_WAIT_L(n) asm volatile("s_waitcnt lgkmcnt(" #n ")" ::: "memory")
; #define PG8_BAR __builtin_amdgcn_s_barrier()
; #define PG8_SCHED __builtin_amdgcn_sched_barrier(0)
; template <class Epi, class Order = StaticOrder, bool HALFN = false>
; __device__ __forceinline__ void gemm_phase(LAS unsigned char* lds, const Gemm g, const Epi& E) {
;     ...
;             PG8_WAIT_V(8); PG8_WAIT_L(0); PG8_BAR; PG8_MMA(1, 0, At, B0); if constexpr (!HALFN) PG8_MMA(1, 1, At, B1); PG8_BAR; PG8_SCHED;
;             PG8_LDB(B0, 1, 0); if constexpr (!HALFN) PG8_LDB(B1, 1, 1); PG8_SCHED; PG8_LDA(At, 1, 0); PG8_STAGE(PG8_SA(0, 1), a2 + hstepA, voffA);
;             PG8_WAIT_V(8); PG8_WAIT_L(0); PG8_BAR; PG8_MMA(0, 0, At, B0); if constexpr (!HALFN) PG8_MMA(0, 1, At, B1); PG8_BAR; PG8_SCHED;
;             PG8_LDA(At, 1, 1); PG8_STAGE(PG8_SB(1, 0), b3, voffB); PG8_STAGE(PG8_SB(1, 1), b3 + hstepB, voffB); PG8_STAGE(PG8_SA(1, 0), a3, voffA);
;             PG8_WAIT_V(8); PG8_WAIT_L(0); PG8_BAR; PG8_MMA(1, 0, At, B0); if constexpr (!HALFN) PG8_MMA(1, 1, At, B1); PG8_BAR; PG8_SCHED;
;         }
	s_add_i32 s34, 0, 0x18000
	v_add_u32_e32 v78, s34, v81
	ds_read_b128 v[84:87], v78
	ds_read_b128 v[88:91], v78 offset:1024
	ds_read_b128 v[92:95], v78 offset:2048
	ds_read_b128 v[96:99], v78 offset:3072
	s_add_u32 s8, s8, 0x80000
	s_addc_u32 s9, s9, 0
	s_mov_b32 m0, s20
	v_lshl_add_u64 v[140:141], s[8:9], 0, v[66:67]
	ds_read_b128 v[100:103], v83 offset:32768
	ds_read_b128 v[104:107], v83 offset:33792
	ds_read_b128 v[108:111], v83 offset:34816
	ds_read_b128 v[112:115], v83 offset:35840
	ds_read_b128 v[116:119], v83 offset:36864
	ds_read_b128 v[120:123], v83 offset:37888
	ds_read_b128 v[124:127], v83 offset:38912
	ds_read_b128 v[128:131], v83 offset:39936
	global_load_lds_dwordx4 v[140:141], off
	v_lshl_add_u64 v[140:141], s[8:9], 0, v[70:71]
	s_mov_b32 m0, s21
	s_nop 0
	global_load_lds_dwordx4 v[140:141], off
	s_waitcnt vmcnt(6)
	s_waitcnt lgkmcnt(0)
	s_barrier
	s_setprio 1
	s_waitcnt lgkmcnt(0)
	v_mfma_f32_16x16x32_bf16 v[62:65], v[84:87], v[100:103], v[62:65]
	v_mfma_f32_16x16x32_bf16 v[58:61], v[92:95], v[100:103], v[58:61]
	v_mfma_f32_16x16x32_bf16 v[54:57], v[84:87], v[108:111], v[54:57]
	v_mfma_f32_16x16x32_bf16 v[50:53], v[92:95], v[108:111], v[50:53]
	v_mfma_f32_16x16x32_bf16 v[46:49], v[84:87], v[116:119], v[46:49]
	v_mfma_f32_16x16x32_bf16 v[42:45], v[92:95], v[116:119], v[42:45]
	v_mfma_f32_16x16x32_bf16 v[38:41], v[84:87], v[124:127], v[38:41]
	v_mfma_f32_16x16x32_bf16 v[34:37], v[92:95], v[124:127], v[34:37]
	v_mfma_f32_16x16x32_bf16 v[62:65], v[88:91], v[104:107], v[62:65]
	v_mfma_f32_16x16x32_bf16 v[58:61], v[96:99], v[104:107], v[58:61]
	v_mfma_f32_16x16x32_bf16 v[54:57], v[88:91], v[112:115], v[54:57]
	v_mfma_f32_16x16x32_bf16 v[50:53], v[96:99], v[112:115], v[50:53]
	v_mfma_f32_16x16x32_bf16 v[46:49], v[88:91], v[120:123], v[46:49]
	v_mfma_f32_16x16x32_bf16 v[42:45], v[96:99], v[120:123], v[42:45]
	v_mfma_f32_16x16x32_bf16 v[38:41], v[88:91], v[128:131], v[38:41]
	v_mfma_f32_16x16x32_bf16 v[34:37], v[96:99], v[128:131], v[34:37]
	s_setprio 0
	s_barrier
	s_add_i32 s8, s34, s15
	v_lshl_add_u64 v[132:133], v[132:133], 0, s[60:61]
	s_mov_b32 m0, s8
	ds_read_b128 v[100:103], v83 offset:49152
	ds_read_b128 v[104:107], v83 offset:50176
	ds_read_b128 v[108:111], v83 offset:51200
	ds_read_b128 v[112:115], v83 offset:52224
	ds_read_b128 v[116:119], v83 offset:53248
	ds_read_b128 v[120:123], v83 offset:54272
	ds_read_b128 v[124:127], v83 offset:55296
	ds_read_b128 v[128:131], v83 offset:56320
	global_load_lds_dwordx4 v[132:133], off
	s_add_i32 m0, s8, 0x2000
	s_add_u32 s4, s4, 0x80080
	v_lshl_add_u64 v[132:133], v[134:135], 0, s[60:61]
	s_addc_u32 s5, s5, 0
	global_load_lds_dwordx4 v[132:133], off
	v_lshl_add_u64 v[132:133], v[136:137], 0, s[60:61]
	s_mov_b32 m0, s51
	s_nop 0
	global_load_lds_dwordx4 v[132:133], off
	v_lshl_add_u64 v[132:133], v[138:139], 0, s[60:61]
	s_mov_b32 m0, s53
	s_nop 0
	global_load_lds_dwordx4 v[132:133], off
	s_waitcnt vmcnt(6)
	s_waitcnt lgkmcnt(0)
	s_barrier
	s_setprio 1
	s_waitcnt lgkmcnt(0)
	v_mfma_f32_16x16x32_bf16 v[30:33], v[84:87], v[100:103], v[30:33]
	v_mfma_f32_16x16x32_bf16 v[26:29], v[92:95], v[100:103], v[26:29]
	v_mfma_f32_16x16x32_bf16 v[22:25], v[84:87], v[108:111], v[22:25]
	v_mfma_f32_16x16x32_bf16 v[18:21], v[92:95], v[108:111], v[18:21]
	v_mfma_f32_16x16x32_bf16 v[14:17], v[84:87], v[116:119], v[14:17]
	v_mfma_f32_16x16x32_bf16 v[10:13], v[92:95], v[116:119], v[10:13]
	v_mfma_f32_16x16x32_bf16 v[6:9], v[84:87], v[124:127], v[6:9]
	v_mfma_f32_16x16x32_bf16 v[2:5], v[92:95], v[124:127], v[2:5]
	v_mfma_f32_16x16x32_bf16 v[30:33], v[88:91], v[104:107], v[30:33]
	v_mfma_f32_16x16x32_bf16 v[26:29], v[96:99], v[104:107], v[26:29]
	v_mfma_f32_16x16x32_bf16 v[22:25], v[88:91], v[112:115], v[22:25]
	v_mfma_f32_16x16x32_bf16 v[18:21], v[96:99], v[112:115], v[18:21]
	v_mfma_f32_16x16x32_bf16 v[14:17], v[88:91], v[120:123], v[14:17]
	v_mfma_f32_16x16x32_bf16 v[10:13], v[96:99], v[120:123], v[10:13]
	v_mfma_f32_16x16x32_bf16 v[6:9], v[88:91], v[128:131], v[6:9]
	v_mfma_f32_16x16x32_bf16 v[2:5], v[96:99], v[128:131], v[2:5]
	s_setprio 0
	s_barrier
	s_add_i32 s31, s31, 2
	s_add_u32 vcc_lo, vcc_lo, 0x100
	s_addc_u32 vcc_hi, vcc_hi, 0
	s_add_u32 s29, s29, 0x100
	s_addc_u32 s30, s30, 0
	s_cmp_gt_u32 s31, 29
	s_cbranch_scc0 .LBB0_239
	s_and_b64 vcc, exec, s[48:49]
	s_cbranch_vccz .LBB0_242
	s_barrier
